# B pair loop: LDS staging stores moved 2 MFMAs before the loop end (on top of D)
# speedup vs baseline: 1.0072x; 1.0072x over previous
; #define AP_GLOAD_K(j, t) do { const char* kt_ = (const char*)Kb + (size_t)AP_CL(t) * 64 * kpitch * 2; \
;     _Pragma("unroll") for (int i_ = 0; i_ < KPT; ++i_) { if (i_ + 1 < KPT || kact1) kreg[j][i_] = *(const u32x4*)(kt_ + kgo[i_]); } } while (0)
; #define AP_GLOAD_V(j, t) do { const char* vt_ = (const char*)Vb + (size_t)AP_CL(t) * 64 * vpitch * 2; \
;     _Pragma("unroll") for (int i_ = 0; i_ < VPT; ++i_) vreg[j][i_] = *(const u32x4*)(vt_ + vgo[i_]); } while (0)
; template <int KW, int DQK, int DV>
; DI void attn_dense_pair(LAS unsigned char* lds, const int tid, const bf16_t* Qw, int qpitch, const bf16_t* Kb, int kpitch, const bf16_t* Vb, int vpitch,
;                         float nbound, f32x16 (&o)[DV / 32], float& l_out) {
;     ...
;     for (int t = 1; t + 1 < NT; t += 2) {
;         AP_GLOAD_K(0, t + 2); AP_GLOAD_K(1, t + 3); AP_GLOAD_V(0, t + 1); AP_GLOAD_V(1, t + 2);
;         f32x16 pn0, pn1;
;         __builtin_amdgcn_sched_barrier(0);
;         tile_step<DQK, KP, DV, VP, true, 4, true>(pw, pn0, pn1, cvec, ls, o, qf, lds + (t & 3) * KT + koff, lds + ((t - 1) & 3) * VT + voff, &osum, onesf);
;         __builtin_amdgcn_sched_barrier(0);
;         tile_step<DQK, KP, DV, VP, true, 4, true>(pw, pn0, pn1, cvec, ls, o, qf, lds + ((t + 1) & 3) * KT + koff, lds + (t & 3) * VT + voff, &osum, onesf);
.LBB0_383:
	s_add_i32 s9, s34, 1
	s_add_i32 s8, s34, 2
	s_add_i32 s29, s34, -1
	s_add_i32 s14, s6, 0x8000
	s_cmpk_lt_u32 s34, 0x7d
	s_cselect_b64 s[0:1], -1, 0
	s_and_b64 vcc, s[0:1], exec
	v_lshl_add_u64 v[80:81], v[178:179], 0, s[6:7]
	s_cselect_b32 s14, s14, 0xfe000
	v_lshl_add_u64 v[82:83], v[176:177], 0, s[14:15]
	global_load_dwordx4 v[162:165], v[80:81], off
	global_load_dwordx4 v[150:153], v[82:83], off
	v_add_co_u32_e64 v80, s[0:1], s70, v180
	s_nop 1
	v_addc_co_u32_e64 v81, s[0:1], 0, v181, s[0:1]
	global_load_dwordx4 v[154:157], v[180:181], off
	global_load_dwordx4 v[158:161], v[80:81], off
	s_and_b32 s1, s34, 3
	s_mul_i32 s0, s1, 0x2400
	v_add_u32_e32 v175, s0, v183
	ds_read_b128 v[80:83], v175
	ds_read_b128 v[194:197], v175 offset:32
	ds_read_b128 v[198:201], v175 offset:4608
	ds_read_b128 v[202:205], v175 offset:4640
	s_and_b32 s0, s29, 3
	s_mul_i32 s14, s0, 0x3000
	v_add_u32_e32 v186, s14, v185
	ds_read_b128 v[206:209], v175 offset:64
	ds_read_b64_tr_b16 v[222:223], v186 offset:36864
	ds_read_b64_tr_b16 v[224:225], v186 offset:38400
	s_waitcnt lgkmcnt(6)
	v_mfma_f32_32x32x16_bf16 v[96:111], v[80:83], v[130:133], v[64:79]
	s_waitcnt lgkmcnt(4)
	v_mfma_f32_32x32x16_bf16 v[80:95], v[198:201], v[130:133], v[64:79]
	ds_read_b128 v[198:201], v175 offset:4672
	ds_read_b64_tr_b16 v[226:227], v186 offset:36928
	ds_read_b64_tr_b16 v[228:229], v186 offset:38464
	v_mfma_f32_32x32x16_bf16 v[48:63], v[112:115], v[146:149], v[48:63]
	v_mfma_f32_32x32x16_bf16 v[96:111], v[194:197], v[124:127], v[96:111]
	ds_read_b128 v[194:197], v175 offset:96
	ds_read_b64_tr_b16 v[230:231], v186 offset:39936
	ds_read_b64_tr_b16 v[232:233], v186 offset:41472
	s_waitcnt lgkmcnt(9)
	v_mfma_f32_32x32x16_bf16 v[80:95], v[202:205], v[124:127], v[80:95]
	ds_read_b128 v[202:205], v175 offset:4704
	ds_read_b64_tr_b16 v[234:235], v186 offset:40000
	ds_read_b64_tr_b16 v[236:237], v186 offset:41536
	v_mfma_f32_32x32x16_bf16 v[48:63], v[112:115], v[142:145], v[48:63]
	s_waitcnt lgkmcnt(11)
	v_mfma_f32_32x32x16_bf16 v[96:111], v[206:209], v[120:123], v[96:111]
	ds_read_b64_tr_b16 v[206:207], v186 offset:43008
	ds_read_b64_tr_b16 v[208:209], v186 offset:44544
	s_waitcnt lgkmcnt(10)
	v_mfma_f32_32x32x16_bf16 v[80:95], v[198:201], v[120:123], v[80:95]
	ds_read_b64_tr_b16 v[198:199], v186 offset:43072
	ds_read_b64_tr_b16 v[200:201], v186 offset:44608
	v_mfma_f32_32x32x16_bf16 v[48:63], v[112:115], v[138:141], v[48:63]
	s_waitcnt lgkmcnt(9)
	v_mfma_f32_32x32x16_bf16 v[96:111], v[194:197], v[116:119], v[96:111]
	ds_read_b64_tr_b16 v[194:195], v186 offset:46080
	ds_read_b64_tr_b16 v[196:197], v186 offset:47616
	s_waitcnt lgkmcnt(8)
	v_mfma_f32_32x32x16_bf16 v[80:95], v[202:205], v[116:119], v[80:95]
	ds_read_b64_tr_b16 v[202:203], v186 offset:46144
	ds_read_b64_tr_b16 v[204:205], v186 offset:47680
	v_mfma_f32_32x32x16_bf16 v[48:63], v[112:115], v[134:137], v[48:63]
	v_mfma_f32_32x32x16_bf16 v[32:47], v[222:225], v[146:149], v[32:47]
	s_nop 3
	v_exp_f32_e32 v96, v96
	v_exp_f32_e32 v97, v97
	v_exp_f32_e32 v98, v98
	v_exp_f32_e32 v99, v99
	v_mfma_f32_32x32x16_bf16 v[16:31], v[226:229], v[146:149], v[16:31]
	v_exp_f32_e32 v100, v100
	v_exp_f32_e32 v101, v101
	v_exp_f32_e32 v102, v102
	v_exp_f32_e32 v103, v103
	v_mfma_f32_32x32x16_bf16 v[32:47], v[230:233], v[142:145], v[32:47]
	v_exp_f32_e32 v104, v104
	v_exp_f32_e32 v105, v105
	v_exp_f32_e32 v106, v106
	v_exp_f32_e32 v107, v107
	s_waitcnt lgkmcnt(8)
	v_mfma_f32_32x32x16_bf16 v[16:31], v[234:237], v[142:145], v[16:31]
	v_exp_f32_e32 v108, v108
	v_exp_f32_e32 v109, v109
	v_exp_f32_e32 v110, v110
	v_exp_f32_e32 v111, v111
	s_waitcnt lgkmcnt(6)
	v_mfma_f32_32x32x16_bf16 v[32:47], v[206:209], v[138:141], v[32:47]
	v_exp_f32_e32 v80, v80
	v_exp_f32_e32 v81, v81
	v_exp_f32_e32 v82, v82
	v_exp_f32_e32 v83, v83
	s_waitcnt lgkmcnt(4)
	v_mfma_f32_32x32x16_bf16 v[16:31], v[198:201], v[138:141], v[16:31]
	v_exp_f32_e32 v84, v84
	v_exp_f32_e32 v85, v85
	v_exp_f32_e32 v86, v86
	v_exp_f32_e32 v87, v87
	s_waitcnt lgkmcnt(2)
	v_mfma_f32_32x32x16_bf16 v[32:47], v[194:197], v[134:137], v[32:47]
	v_exp_f32_e32 v88, v88
	v_exp_f32_e32 v89, v89
	v_exp_f32_e32 v90, v90
	v_exp_f32_e32 v91, v91
	s_waitcnt lgkmcnt(0)
	v_mfma_f32_32x32x16_bf16 v[16:31], v[202:205], v[134:137], v[16:31]
	v_cvt_pk_bf16_f32 v135, v90, v91
	v_cvt_pk_bf16_f32 v134, v88, v89
	v_cvt_pk_bf16_f32 v141, v86, v87
	v_cvt_pk_bf16_f32 v140, v84, v85
	v_cvt_pk_bf16_f32 v139, v82, v83
	v_cvt_pk_bf16_f32 v138, v80, v81
	v_cvt_pk_bf16_f32 v145, v110, v111
	v_cvt_pk_bf16_f32 v144, v108, v109
	v_cvt_pk_bf16_f32 v143, v106, v107
	v_cvt_pk_bf16_f32 v142, v104, v105
	v_cvt_pk_bf16_f32 v149, v102, v103
	v_cvt_pk_bf16_f32 v148, v100, v101
	v_cvt_pk_bf16_f32 v147, v98, v99
	v_cvt_pk_bf16_f32 v146, v96, v97
	v_exp_f32_e32 v92, v92
	v_exp_f32_e32 v93, v93
	v_exp_f32_e32 v94, v94
	v_exp_f32_e32 v95, v95
	v_cvt_pk_bf16_f32 v136, v92, v93
	v_cvt_pk_bf16_f32 v137, v94, v95
	s_and_b32 s9, s9, 3
	s_mul_i32 s14, s9, 0x2400
	v_add_u32_e32 v175, s14, v183
	ds_read_b128 v[80:83], v175
	ds_read_b128 v[194:197], v175 offset:32
	ds_read_b128 v[198:201], v175 offset:4608
	ds_read_b128 v[202:205], v175 offset:4640
	s_mulk_i32 s1, 0x3000
	v_add_u32_e32 v186, s1, v185
	ds_read_b128 v[206:209], v175 offset:64
	ds_read_b64_tr_b16 v[222:223], v186 offset:36864
	ds_read_b64_tr_b16 v[224:225], v186 offset:38400
	s_waitcnt lgkmcnt(6)
	v_mfma_f32_32x32x16_bf16 v[96:111], v[80:83], v[130:133], v[64:79]
	s_waitcnt lgkmcnt(4)
; #define AP_LSTORE_K(j, t) do { \
;     _Pragma("unroll") for (int i_ = 0; i_ < KPT; ++i_) { if (i_ + 1 < KPT || kact1) *(LAS u32x4*)(lds + ((t) & 3) * KT + klo[i_]) = kreg[j][i_]; } } while (0)
; #define AP_LSTORE_V(j, t) do { \
;     _Pragma("unroll") for (int i_ = 0; i_ < VPT; ++i_) *(LAS u32x4*)(lds + ((t) & 3) * VT + vlo[i_]) = vreg[j][i_]; } while (0)
; template <int KW, int DQK, int DV>
; DI void attn_dense_pair(LAS unsigned char* lds, const int tid, const bf16_t* Qw, int qpitch, const bf16_t* Kb, int kpitch, const bf16_t* Vb, int vpitch,
;                         float nbound, f32x16 (&o)[DV / 32], float& l_out) {
;     ...
;         tile_step<DQK, KP, DV, VP, true, 4, true>(pw, pn0, pn1, cvec, ls, o, qf, lds + (t & 3) * KT + koff, lds + ((t - 1) & 3) * VT + voff, &osum, onesf);
;         __builtin_amdgcn_sched_barrier(0);
;         tile_step<DQK, KP, DV, VP, true, 4, true>(pw, pn0, pn1, cvec, ls, o, qf, lds + ((t + 1) & 3) * KT + koff, lds + (t & 3) * VT + voff, &osum, onesf);
;         AP_LSTORE_K(0, t + 2); AP_LSTORE_K(1, t + 3); AP_LSTORE_V(0, t + 1); AP_LSTORE_V(1, t + 2);
;         __syncthreads();
	v_mfma_f32_32x32x16_bf16 v[80:95], v[198:201], v[130:133], v[64:79]
	ds_read_b128 v[198:201], v175 offset:4672
	ds_read_b64_tr_b16 v[226:227], v186 offset:36928
	ds_read_b64_tr_b16 v[228:229], v186 offset:38464
	v_mfma_f32_32x32x16_bf16 v[48:63], v[112:115], v[146:149], v[48:63]
	v_mfma_f32_32x32x16_bf16 v[96:111], v[194:197], v[124:127], v[96:111]
	ds_read_b128 v[194:197], v175 offset:96
	ds_read_b64_tr_b16 v[230:231], v186 offset:39936
	ds_read_b64_tr_b16 v[232:233], v186 offset:41472
	s_waitcnt lgkmcnt(9)
	v_mfma_f32_32x32x16_bf16 v[80:95], v[202:205], v[124:127], v[80:95]
	ds_read_b128 v[202:205], v175 offset:4704
	ds_read_b64_tr_b16 v[234:235], v186 offset:40000
	ds_read_b64_tr_b16 v[236:237], v186 offset:41536
	v_mfma_f32_32x32x16_bf16 v[48:63], v[112:115], v[142:145], v[48:63]
	s_waitcnt lgkmcnt(11)
	v_mfma_f32_32x32x16_bf16 v[96:111], v[206:209], v[120:123], v[96:111]
	ds_read_b64_tr_b16 v[206:207], v186 offset:43008
	ds_read_b64_tr_b16 v[208:209], v186 offset:44544
	s_waitcnt lgkmcnt(10)
	v_mfma_f32_32x32x16_bf16 v[80:95], v[198:201], v[120:123], v[80:95]
	ds_read_b64_tr_b16 v[198:199], v186 offset:43072
	ds_read_b64_tr_b16 v[200:201], v186 offset:44608
	v_mfma_f32_32x32x16_bf16 v[48:63], v[112:115], v[138:141], v[48:63]
	s_waitcnt lgkmcnt(9)
	v_mfma_f32_32x32x16_bf16 v[96:111], v[194:197], v[116:119], v[96:111]
	ds_read_b64_tr_b16 v[194:195], v186 offset:46080
	ds_read_b64_tr_b16 v[196:197], v186 offset:47616
	s_waitcnt lgkmcnt(8)
	v_mfma_f32_32x32x16_bf16 v[80:95], v[202:205], v[116:119], v[80:95]
	ds_read_b64_tr_b16 v[202:203], v186 offset:46144
	ds_read_b64_tr_b16 v[204:205], v186 offset:47680
	v_mfma_f32_32x32x16_bf16 v[48:63], v[112:115], v[134:137], v[48:63]
	v_mfma_f32_32x32x16_bf16 v[32:47], v[222:225], v[146:149], v[32:47]
	s_nop 3
	v_exp_f32_e32 v96, v96
	v_exp_f32_e32 v97, v97
	v_exp_f32_e32 v98, v98
	v_exp_f32_e32 v99, v99
	v_mfma_f32_32x32x16_bf16 v[16:31], v[226:229], v[146:149], v[16:31]
	v_exp_f32_e32 v100, v100
	v_exp_f32_e32 v101, v101
	v_exp_f32_e32 v102, v102
	v_exp_f32_e32 v103, v103
	v_mfma_f32_32x32x16_bf16 v[32:47], v[230:233], v[142:145], v[32:47]
	v_exp_f32_e32 v104, v104
	v_exp_f32_e32 v105, v105
	v_exp_f32_e32 v106, v106
	v_exp_f32_e32 v107, v107
	s_waitcnt lgkmcnt(8)
	v_mfma_f32_32x32x16_bf16 v[16:31], v[234:237], v[142:145], v[16:31]
	v_exp_f32_e32 v108, v108
	v_exp_f32_e32 v109, v109
	v_exp_f32_e32 v110, v110
	v_exp_f32_e32 v111, v111
	s_waitcnt lgkmcnt(6)
	v_mfma_f32_32x32x16_bf16 v[32:47], v[206:209], v[138:141], v[32:47]
	v_exp_f32_e32 v80, v80
	v_exp_f32_e32 v81, v81
	v_exp_f32_e32 v82, v82
	v_exp_f32_e32 v83, v83
	s_waitcnt lgkmcnt(4)
	v_mfma_f32_32x32x16_bf16 v[16:31], v[198:201], v[138:141], v[16:31]
	v_exp_f32_e32 v84, v84
	v_exp_f32_e32 v85, v85
	v_exp_f32_e32 v86, v86
	v_exp_f32_e32 v87, v87
	s_waitcnt lgkmcnt(2)
	v_mfma_f32_32x32x16_bf16 v[32:47], v[194:197], v[134:137], v[32:47]
	s_and_b32 s1, s8, 3
	s_mul_i32 s14, s1, 0x2400
	v_add_u32_e32 v186, s14, v182
	s_mulk_i32 s0, 0x2400
	s_waitcnt vmcnt(3)
	ds_write_b128 v186, v[162:165]
	v_add_u32_e32 v186, s0, v182
	s_mulk_i32 s9, 0x3000
	s_waitcnt vmcnt(2)
	ds_write_b128 v186, v[150:153]
	v_add_u32_e32 v186, s9, v184
	s_mulk_i32 s1, 0x3000
	s_waitcnt vmcnt(1)
	ds_write_b128 v186, v[154:157] offset:36864
	v_add_u32_e32 v186, s1, v184
	s_waitcnt vmcnt(0)
	ds_write_b128 v186, v[158:161] offset:36864
	v_exp_f32_e32 v88, v88
	v_exp_f32_e32 v89, v89
	v_exp_f32_e32 v90, v90
	v_exp_f32_e32 v91, v91
	s_waitcnt lgkmcnt(4)
	v_mfma_f32_32x32x16_bf16 v[16:31], v[202:205], v[134:137], v[16:31]
	v_cvt_pk_bf16_f32 v135, v90, v91
	v_cvt_pk_bf16_f32 v134, v88, v89
	v_cvt_pk_bf16_f32 v141, v86, v87
	v_cvt_pk_bf16_f32 v140, v84, v85
	v_cvt_pk_bf16_f32 v139, v82, v83
	v_cvt_pk_bf16_f32 v138, v80, v81
	v_cvt_pk_bf16_f32 v145, v110, v111
	v_cvt_pk_bf16_f32 v144, v108, v109
	v_cvt_pk_bf16_f32 v143, v106, v107
	v_cvt_pk_bf16_f32 v142, v104, v105
	v_cvt_pk_bf16_f32 v149, v102, v103
	v_cvt_pk_bf16_f32 v148, v100, v101
	v_cvt_pk_bf16_f32 v147, v98, v99
	v_cvt_pk_bf16_f32 v146, v96, v97
	v_exp_f32_e32 v92, v92
	v_exp_f32_e32 v93, v93
	v_exp_f32_e32 v94, v94
	v_exp_f32_e32 v95, v95
	s_mov_b64 s[0:1], 0x460000
	s_add_u32 s6, s6, 0x4000
	v_cvt_pk_bf16_f32 v136, v92, v93
	v_cvt_pk_bf16_f32 v137, v94, v95
	v_lshl_add_u64 v[180:181], v[180:181], 0, s[0:1]
	s_addc_u32 s7, s7, 0
	s_mov_b32 s34, s8
	s_waitcnt lgkmcnt(0)
	s_barrier
	s_cbranch_vccnz .LBB0_383
; template <int KW, int DQK, int DV>
; DI void attn_dense_pair(LAS unsigned char* lds, const int tid, const bf16_t* Qw, int qpitch, const bf16_t* Kb, int kpitch, const bf16_t* Vb, int vpitch,
;                         float nbound, f32x16 (&o)[DV / 32], float& l_out) {
;     ...
;     { f32x16 pn0, pn1;
;       tile_step<DQK, KP, DV, VP, true, 4, true>(pw, pn0, pn1, cvec, ls, o, qf, lds + ((NT - 1) & 3) * KT + koff, lds + ((NT - 2) & 3) * VT + voff, &osum, onesf); }
;     rowsum_pw(pw, ls);
;     pv_tile<DV, VP>(o, pw, lds + ((NT - 1) & 3) * VT + voff);
;     float l = (ls[0] + ls[1]) + (ls[2] + ls[3]);
;     __syncthreads();
	ds_read_b128 v[96:99], v183 offset:27648
	ds_read_b128 v[100:103], v183 offset:27680
	ds_read_b128 v[104:107], v183 offset:32256
	ds_read_b128 v[108:111], v183 offset:32288
	s_waitcnt lgkmcnt(3)
	v_mfma_f32_32x32x16_bf16 v[80:95], v[96:99], v[130:133], v[64:79]
	ds_read_b128 v[96:99], v183 offset:27712
	ds_read_b64_tr_b16 v[150:151], v185 offset:61440
	ds_read_b64_tr_b16 v[152:153], v185 offset:62976
	s_waitcnt lgkmcnt(4)
	v_mfma_f32_32x32x16_bf16 v[64:79], v[104:107], v[130:133], v[64:79]
	ds_read_b128 v[104:107], v183 offset:32320
	ds_read_b64_tr_b16 v[130:131], v185 offset:61504
	ds_read_b64_tr_b16 v[132:133], v185 offset:63040
	v_mfma_f32_32x32x16_bf16 v[48:63], v[112:115], v[146:149], v[48:63]
	v_mfma_f32_32x32x16_bf16 v[80:95], v[100:103], v[124:127], v[80:95]
	ds_read_b128 v[100:103], v183 offset:27744
	ds_read_b64_tr_b16 v[154:155], v185 offset:64512
	ds_read_b64_tr_b16 v[156:157], v190 offset:4608
	s_waitcnt lgkmcnt(9)
	v_mfma_f32_32x32x16_bf16 v[64:79], v[108:111], v[124:127], v[64:79]
	ds_read_b128 v[108:111], v183 offset:32352
	ds_read_b64_tr_b16 v[124:125], v185 offset:64576
	ds_read_b64_tr_b16 v[126:127], v190 offset:4672
	v_mfma_f32_32x32x16_bf16 v[48:63], v[112:115], v[142:145], v[48:63]
	s_waitcnt lgkmcnt(11)
	v_mfma_f32_32x32x16_bf16 v[80:95], v[96:99], v[120:123], v[80:95]
	ds_read_b64_tr_b16 v[96:97], v190 offset:6144
	ds_read_b64_tr_b16 v[98:99], v190 offset:7680
	s_waitcnt lgkmcnt(10)
	v_mfma_f32_32x32x16_bf16 v[64:79], v[104:107], v[120:123], v[64:79]
	ds_read_b64_tr_b16 v[104:105], v190 offset:6208
	ds_read_b64_tr_b16 v[106:107], v190 offset:7744
	v_mfma_f32_32x32x16_bf16 v[48:63], v[112:115], v[138:141], v[48:63]
	s_waitcnt lgkmcnt(9)
	v_mfma_f32_32x32x16_bf16 v[80:95], v[100:103], v[116:119], v[80:95]
	ds_read_b64_tr_b16 v[100:101], v190 offset:9216
	ds_read_b64_tr_b16 v[102:103], v190 offset:10752
	s_waitcnt lgkmcnt(8)
	v_mfma_f32_32x32x16_bf16 v[64:79], v[108:111], v[116:119], v[64:79]
	ds_read_b64_tr_b16 v[108:109], v190 offset:9280
	ds_read_b64_tr_b16 v[110:111], v190 offset:10816
	v_mfma_f32_32x32x16_bf16 v[48:63], v[112:115], v[134:137], v[48:63]
	v_mfma_f32_32x32x16_bf16 v[32:47], v[150:153], v[146:149], v[32:47]
	s_nop 10
	v_exp_f32_e32 v49, v80
	v_exp_f32_e32 v52, v81
	v_exp_f32_e32 v53, v82
	v_exp_f32_e32 v62, v83
	v_mfma_f32_32x32x16_bf16 v[16:31], v[130:133], v[146:149], v[16:31]
	v_exp_f32_e32 v63, v84
	v_exp_f32_e32 v80, v85
	v_exp_f32_e32 v81, v86
	v_exp_f32_e32 v82, v87
	v_mfma_f32_32x32x16_bf16 v[32:47], v[154:157], v[142:145], v[32:47]
	v_exp_f32_e32 v58, v88
	v_exp_f32_e32 v83, v89
	v_exp_f32_e32 v59, v90
	v_exp_f32_e32 v84, v91
	s_waitcnt lgkmcnt(8)
	v_mfma_f32_32x32x16_bf16 v[16:31], v[124:127], v[142:145], v[16:31]
	v_exp_f32_e32 v60, v92
	v_exp_f32_e32 v85, v93
	v_exp_f32_e32 v61, v94
	v_exp_f32_e32 v86, v95
	s_waitcnt lgkmcnt(6)
	v_mfma_f32_32x32x16_bf16 v[32:47], v[96:99], v[138:141], v[32:47]
	v_exp_f32_e32 v54, v64
	v_exp_f32_e32 v64, v65
	v_exp_f32_e32 v55, v66
	v_exp_f32_e32 v65, v67
	s_waitcnt lgkmcnt(4)
	v_mfma_f32_32x32x16_bf16 v[16:31], v[104:107], v[138:141], v[16:31]
	v_exp_f32_e32 v56, v68
	v_exp_f32_e32 v66, v69
	v_exp_f32_e32 v57, v70
	v_exp_f32_e32 v67, v71
	s_waitcnt lgkmcnt(2)
	v_mfma_f32_32x32x16_bf16 v[32:47], v[100:103], v[134:137], v[32:47]
	v_exp_f32_e32 v50, v72
	v_exp_f32_e32 v68, v73
	v_exp_f32_e32 v51, v74
	v_exp_f32_e32 v69, v75
	s_waitcnt lgkmcnt(0)
	v_mfma_f32_32x32x16_bf16 v[16:31], v[108:111], v[134:137], v[16:31]
	v_exp_f32_e32 v101, v76
	v_exp_f32_e32 v106, v77
	v_exp_f32_e32 v107, v78
	v_exp_f32_e32 v108, v79
	v_cvt_pk_bf16_f32 v51, v51, v69
	v_cvt_pk_bf16_f32 v50, v50, v68
	v_cvt_pk_bf16_f32 v57, v57, v67
	v_cvt_pk_bf16_f32 v56, v56, v66
	v_cvt_pk_bf16_f32 v55, v55, v65
	v_cvt_pk_bf16_f32 v54, v54, v64
	v_cvt_pk_bf16_f32 v61, v61, v86
	v_cvt_pk_bf16_f32 v60, v60, v85
	v_cvt_pk_bf16_f32 v59, v59, v84
	v_cvt_pk_bf16_f32 v58, v58, v83
	v_cvt_pk_bf16_f32 v69, v81, v82
	v_cvt_pk_bf16_f32 v68, v63, v80
	v_cvt_pk_bf16_f32 v67, v53, v62
	v_cvt_pk_bf16_f32 v66, v49, v52
	v_mov_b32_e32 v49, v252
	s_mov_b32 s0, s20
	ds_read_b64_tr_b16 v[76:77], v193 offset:36864
	ds_read_b64_tr_b16 v[78:79], v193 offset:38400
	ds_read_b64_tr_b16 v[82:83], v193 offset:38464
	ds_read_b64_tr_b16 v[80:81], v193 offset:36928
	ds_read_b64_tr_b16 v[84:85], v193 offset:39936
	ds_read_b64_tr_b16 v[86:87], v193 offset:41472
	ds_read_b64_tr_b16 v[90:91], v193 offset:41536
	ds_read_b64_tr_b16 v[88:89], v193 offset:40000
	ds_read_b64_tr_b16 v[92:93], v193 offset:43008
	ds_read_b64_tr_b16 v[94:95], v193 offset:44544
	ds_read_b64_tr_b16 v[72:73], v193 offset:44608
	ds_read_b64_tr_b16 v[70:71], v193 offset:43072
	ds_read_b64_tr_b16 v[96:97], v193 offset:46080
	ds_read_b64_tr_b16 v[98:99], v193 offset:47616
	ds_read_b64_tr_b16 v[64:65], v193 offset:47680
	ds_read_b64_tr_b16 v[62:63], v193 offset:46144
	s_waitcnt lgkmcnt(0)
	s_barrier
; DI float bflo(unsigned u) { return __uint_as_float(u << 16); }
; DI float bfhi(unsigned u) { return __uint_as_float(u & 0xffff0000u); }
; DI float shx(float v, int m, int lane) { return __int_as_float(__builtin_amdgcn_ds_bpermute((lane ^ m) << 2, __float_as_int(v))); }
; template <int KW, int DQK, int DV>
; DI void attn_dense_pair(LAS unsigned char* lds, const int tid, const bf16_t* Qw, int qpitch, const bf16_t* Kb, int kpitch, const bf16_t* Vb, int vpitch,
;                         float nbound, f32x16 (&o)[DV / 32], float& l_out) {
;     ...
;     rowsum_pw(pw, ls);
;     pv_tile<DV, VP>(o, pw, lds + ((NT - 1) & 3) * VT + voff);
;     float l = (ls[0] + ls[1]) + (ls[2] + ls[3]);
;     __syncthreads();
;     ...
;     l += shx(l, 32, lane);
;     l += __int_as_float(__builtin_amdgcn_ds_bpermute((lane & 31) << 2, __float_as_int(osum[0])));
;     l_out = l;
; DI void store_y64(const f32x16 (&o)[2], float linv, bf16_t* Y, const bf16_t* proj, int token, int ycol, int hi) {
; #pragma unroll
;     for (int d0 = 0; d0 < 2; ++d0)
; #pragma unroll
;         for (int g = 0; g < 4; ++g) {
;             const int col = ycol + 32 * d0 + 8 * g + 4 * hi;
;             const u32x2 gv = *(const u32x2*)(proj + (size_t)token * LDP + C_SILU + col);
;             u32x2 w;
;             w.x = cvt_pk(o[d0][4 * g + 0] * linv * bflo(gv.x), o[d0][4 * g + 1] * linv * bfhi(gv.x));
;             w.y = cvt_pk(o[d0][4 * g + 2] * linv * bflo(gv.y), o[d0][4 * g + 3] * linv * bfhi(gv.y));
;             *(u32x2*)(Y + (size_t)token * DM + col) = w;
;         }
	s_lshl_b32 s1, s0, 8
	s_and_b32 s1, s1, 0x1f00
	s_add_i32 s1, s1, s21
	v_and_or_b32 v100, v49, 31, s1
	s_lshl_b32 s0, s0, 1
	v_ashrrev_i32_e32 v49, 3, v49
	s_andn2_b32 s0, s0, 63
	v_and_b32_e32 v49, -4, v49
	v_add_u32_e32 v49, s0, v49
	v_add_u32_e32 v52, 0x200, v49
	v_mov_b64_e32 v[74:75], s[2:3]
	v_mad_i64_i32 v[74:75], s[0:1], v100, s68, v[74:75]
	v_ashrrev_i32_e32 v53, 31, v52
	v_lshl_add_u64 v[74:75], v[74:75], 0, s[88:89]
	v_lshlrev_b64 v[102:103], 1, v[52:53]
	v_lshl_add_u64 v[52:53], v[74:75], 0, v[102:103]
	global_load_dwordx2 v[104:105], v[52:53], off
	global_load_dwordx2 v[150:151], v[52:53], off offset:16
	global_load_dwordx2 v[152:153], v[52:53], off offset:32
	global_load_dwordx2 v[154:155], v[52:53], off offset:48
	global_load_dwordx2 v[156:157], v[52:53], off offset:64
	global_load_dwordx2 v[158:159], v[52:53], off offset:80
	global_load_dwordx2 v[160:161], v[52:53], off offset:96
	global_load_dwordx2 v[162:163], v[52:53], off offset:112
	v_mfma_f32_32x32x16_bf16 v[32:47], v[76:79], v[66:69], v[32:47]
	v_cvt_pk_bf16_f32 v52, v101, v106
	v_cvt_pk_bf16_f32 v53, v107, v108
	v_mov_b32_e32 v106, v129
	v_mov_b32_e32 v108, v129
	v_mov_b32_e32 v107, v129
	v_mov_b32_e32 v109, v129
	v_dot2c_f32_bf16_e32 v106, 0x3f803f80, v66
	v_dot2c_f32_bf16_e32 v108, 0x3f803f80, v67
	v_dot2c_f32_bf16_e32 v107, 0x3f803f80, v68
	v_dot2c_f32_bf16_e32 v109, 0x3f803f80, v69
	v_dot2c_f32_bf16_e32 v106, 0x3f803f80, v58
	v_dot2c_f32_bf16_e32 v108, 0x3f803f80, v59
	v_dot2c_f32_bf16_e32 v107, 0x3f803f80, v60
	v_dot2c_f32_bf16_e32 v109, 0x3f803f80, v61
	v_dot2c_f32_bf16_e32 v106, 0x3f803f80, v54
	v_dot2c_f32_bf16_e32 v108, 0x3f803f80, v55
	v_dot2c_f32_bf16_e32 v107, 0x3f803f80, v56
	v_dot2c_f32_bf16_e32 v109, 0x3f803f80, v57
	v_mfma_f32_32x32x16_bf16 v[32:47], v[84:87], v[58:61], v[32:47]
	v_dot2c_f32_bf16_e32 v106, 0x3f803f80, v50
	v_dot2c_f32_bf16_e32 v108, 0x3f803f80, v51
	v_dot2c_f32_bf16_e32 v107, 0x3f803f80, v52
	v_dot2c_f32_bf16_e32 v109, 0x3f803f80, v53
	ds_bpermute_b32 v48, v192, v48
	v_ashrrev_i32_e32 v101, 31, v100
	s_add_i32 s20, s20, s28
	v_pk_add_f32 v[76:77], v[106:107], v[108:109]
	v_mfma_f32_32x32x16_bf16 v[32:47], v[92:95], v[54:57], v[32:47]
	v_add_f32_e32 v76, v76, v77
	ds_bpermute_b32 v77, v191, v76
	s_cmpk_gt_i32 s20, 0xff
	s_waitcnt lgkmcnt(0)
	v_add_f32_e32 v76, v76, v77
	v_add_f32_e32 v48, v76, v48
	v_div_scale_f32 v76, s[0:1], v48, v48, 1.0
	v_rcp_f32_e32 v77, v76
	v_mfma_f32_32x32x16_bf16 v[32:47], v[96:99], v[50:53], v[32:47]
	v_fma_f32 v78, -v76, v77, 1.0
	v_fmac_f32_e32 v77, v78, v77
	v_div_scale_f32 v78, vcc, 1.0, v48, 1.0
	v_mul_f32_e32 v79, v78, v77
	v_fma_f32 v84, -v76, v79, v78
	v_fmac_f32_e32 v79, v84, v77
	v_fma_f32 v76, -v76, v79, v78
	v_div_fmas_f32 v76, v76, v77, v79
	v_div_fixup_f32 v48, v76, v48, 1.0
	s_nop 2
	v_pk_mul_f32 v[32:33], v[32:33], v[48:49] op_sel_hi:[1,0]
	v_lshlrev_b64 v[76:77], 12, v[100:101]
	v_lshl_add_u64 v[76:77], s[4:5], 0, v[76:77]
	v_mfma_f32_32x32x16_bf16 v[16:31], v[80:83], v[66:69], v[16:31]
	v_mul_f32_e64 v36, v36, v48
	v_mul_f32_e64 v37, v37, v48
	v_mul_f32_e64 v38, v38, v48
	v_mul_f32_e64 v39, v39, v48
	s_waitcnt vmcnt(7)
	v_lshlrev_b32_e32 v78, 16, v104
	v_and_b32_e32 v79, 0xffff0000, v104
	v_pk_mul_f32 v[32:33], v[32:33], v[78:79]
	v_mfma_f32_32x32x16_bf16 v[16:31], v[88:91], v[58:61], v[16:31]
	v_cvt_pk_bf16_f32 v78, v32, v33
	v_mul_f32_e64 v32, v34, v48
	v_mul_f32_e64 v33, v35, v48
	v_lshlrev_b32_e32 v34, 16, v105
	v_and_b32_e32 v35, 0xffff0000, v105
	v_pk_mul_f32 v[32:33], v[32:33], v[34:35]
	v_add_u32_e32 v34, 0x208, v49
	v_cvt_pk_bf16_f32 v79, v32, v33
	v_lshl_add_u64 v[32:33], v[76:77], 0, v[102:103]
	v_ashrrev_i32_e32 v35, 31, v34
	global_store_dwordx2 v[32:33], v[78:79], off
	v_lshl_add_u64 v[34:35], v[34:35], 1, v[74:75]
	v_add_u32_e32 v76, 0x210, v49
	v_ashrrev_i32_e32 v77, 31, v76
	v_lshl_add_u64 v[76:77], v[76:77], 1, v[74:75]
	v_mfma_f32_32x32x16_bf16 v[16:31], v[70:73], v[54:57], v[16:31]
	s_waitcnt vmcnt(7)
; DI float bflo(unsigned u) { return __uint_as_float(u << 16); }
; DI float bfhi(unsigned u) { return __uint_as_float(u & 0xffff0000u); }
; #define RELANE(x) int x = (int)__builtin_amdgcn_mbcnt_hi(~0u, __builtin_amdgcn_mbcnt_lo(~0u, 0u)); asm volatile("" : "+v"(x));
; DI void store_y64(const f32x16 (&o)[2], float linv, bf16_t* Y, const bf16_t* proj, int token, int ycol, int hi) {
; #pragma unroll
;     for (int d0 = 0; d0 < 2; ++d0)
; #pragma unroll
;         for (int g = 0; g < 4; ++g) {
;             const int col = ycol + 32 * d0 + 8 * g + 4 * hi;
;             const u32x2 gv = *(const u32x2*)(proj + (size_t)token * LDP + C_SILU + col);
;             u32x2 w;
;             w.x = cvt_pk(o[d0][4 * g + 0] * linv * bflo(gv.x), o[d0][4 * g + 1] * linv * bfhi(gv.x));
;             w.y = cvt_pk(o[d0][4 * g + 2] * linv * bflo(gv.y), o[d0][4 * g + 3] * linv * bfhi(gv.y));
;             *(u32x2*)(Y + (size_t)token * DM + col) = w;
;         }
; __global__ void __launch_bounds__(512) mega(Params P) {
;     ...
;             for (int u = vcu; u < 256; u += G) {
;                 const int h = u >> 5, qb = u & 31, q0 = qb * 256 + wid * 32, kv = h >> 2;
;                 f32x16 o[2]; float lsum;
;                 attn_dense_pair<64, 64, 64>(lds, tid, Qb + ((size_t)h * S + q0) * 64, 64, Kb + (size_t)kv * S * 64, 64, proj + C_BV + kv * 64, LDP, nbound, o, lsum);
;                 { RELANE(l2) int u2 = u; asm volatile("" : "+s"(u2)); const int h2 = u2 >> 5, q02 = (u2 & 31) * 256 + wid * 32;
;                   store_y64(o, 1.0f / lsum, Yb, proj, q02 + (l2 & 31), 512 + h2 * 64, l2 >> 5); }
	v_lshlrev_b32_e32 v66, 16, v150
	v_and_b32_e32 v67, 0xffff0000, v150
	v_lshlrev_b32_e32 v34, 16, v151
	v_and_b32_e32 v35, 0xffff0000, v151
	v_pk_mul_f32 v[36:37], v[36:37], v[66:67]
	v_pk_mul_f32 v[34:35], v[38:39], v[34:35]
	v_cvt_pk_bf16_f32 v36, v36, v37
	v_cvt_pk_bf16_f32 v37, v34, v35
	global_store_dwordx2 v[32:33], v[36:37], off offset:16
	v_pk_mul_f32 v[38:39], v[40:41], v[48:49] op_sel_hi:[1,0]
	v_pk_mul_f32 v[40:41], v[42:43], v[48:49] op_sel_hi:[1,0]
	v_add_u32_e32 v36, 0x218, v49
	v_ashrrev_i32_e32 v37, 31, v36
	v_lshl_add_u64 v[36:37], v[36:37], 1, v[74:75]
	v_mfma_f32_32x32x16_bf16 v[16:31], v[62:65], v[50:53], v[16:31]
	s_waitcnt vmcnt(7)
	v_lshlrev_b32_e32 v42, 16, v152
	v_and_b32_e32 v43, 0xffff0000, v152
	v_lshlrev_b32_e32 v34, 16, v153
	v_and_b32_e32 v35, 0xffff0000, v153
	v_pk_mul_f32 v[38:39], v[38:39], v[42:43]
	v_pk_mul_f32 v[34:35], v[40:41], v[34:35]
	v_cvt_pk_bf16_f32 v38, v38, v39
	v_cvt_pk_bf16_f32 v39, v34, v35
	global_store_dwordx2 v[32:33], v[38:39], off offset:32
	v_pk_mul_f32 v[38:39], v[44:45], v[48:49] op_sel_hi:[1,0]
	v_pk_mul_f32 v[40:41], v[46:47], v[48:49] op_sel_hi:[1,0]
	v_add_u32_e32 v36, 0x220, v49
	v_ashrrev_i32_e32 v37, 31, v36
	v_lshl_add_u64 v[36:37], v[36:37], 1, v[74:75]
	v_pk_mul_f32 v[16:17], v[16:17], v[48:49] op_sel_hi:[1,0]
	v_pk_mul_f32 v[18:19], v[18:19], v[48:49] op_sel_hi:[1,0]
	v_pk_mul_f32 v[20:21], v[20:21], v[48:49] op_sel_hi:[1,0]
	v_pk_mul_f32 v[22:23], v[22:23], v[48:49] op_sel_hi:[1,0]
	s_waitcnt vmcnt(7)
	v_lshlrev_b32_e32 v42, 16, v154
	v_and_b32_e32 v43, 0xffff0000, v154
	v_lshlrev_b32_e32 v34, 16, v155
	v_and_b32_e32 v35, 0xffff0000, v155
	v_pk_mul_f32 v[38:39], v[38:39], v[42:43]
	v_pk_mul_f32 v[34:35], v[40:41], v[34:35]
	v_cvt_pk_bf16_f32 v38, v38, v39
	v_cvt_pk_bf16_f32 v39, v34, v35
	global_store_dwordx2 v[32:33], v[38:39], off offset:48
	v_add_u32_e32 v36, 0x228, v49
	v_ashrrev_i32_e32 v37, 31, v36
	v_lshl_add_u64 v[36:37], v[36:37], 1, v[74:75]
	s_waitcnt vmcnt(7)
	v_lshlrev_b32_e32 v38, 16, v156
	v_and_b32_e32 v39, 0xffff0000, v156
	v_lshlrev_b32_e32 v34, 16, v157
	v_and_b32_e32 v35, 0xffff0000, v157
	v_pk_mul_f32 v[16:17], v[16:17], v[38:39]
	v_pk_mul_f32 v[18:19], v[18:19], v[34:35]
	v_cvt_pk_bf16_f32 v16, v16, v17
	v_cvt_pk_bf16_f32 v17, v18, v19
	global_store_dwordx2 v[32:33], v[16:17], off offset:64
	v_add_u32_e32 v18, 0x230, v49
	v_ashrrev_i32_e32 v19, 31, v18
	v_lshl_add_u64 v[18:19], v[18:19], 1, v[74:75]
	s_waitcnt vmcnt(7)
	v_lshlrev_b32_e32 v34, 16, v158
	v_and_b32_e32 v35, 0xffff0000, v158
	v_lshlrev_b32_e32 v16, 16, v159
	v_and_b32_e32 v17, 0xffff0000, v159
	v_pk_mul_f32 v[20:21], v[20:21], v[34:35]
	v_pk_mul_f32 v[16:17], v[22:23], v[16:17]
	v_cvt_pk_bf16_f32 v20, v20, v21
	v_cvt_pk_bf16_f32 v21, v16, v17
	global_store_dwordx2 v[32:33], v[20:21], off offset:80
	v_pk_mul_f32 v[20:21], v[24:25], v[48:49] op_sel_hi:[1,0]
	v_pk_mul_f32 v[22:23], v[26:27], v[48:49] op_sel_hi:[1,0]
	v_add_u32_e32 v18, 0x238, v49
	v_ashrrev_i32_e32 v19, 31, v18
	v_lshl_add_u64 v[18:19], v[18:19], 1, v[74:75]
	s_waitcnt vmcnt(7)
	v_lshlrev_b32_e32 v24, 16, v160
	v_and_b32_e32 v25, 0xffff0000, v160
	v_lshlrev_b32_e32 v16, 16, v161
	v_and_b32_e32 v17, 0xffff0000, v161
	v_pk_mul_f32 v[20:21], v[20:21], v[24:25]
	v_pk_mul_f32 v[16:17], v[22:23], v[16:17]
	v_cvt_pk_bf16_f32 v20, v20, v21
	v_cvt_pk_bf16_f32 v21, v16, v17
	global_store_dwordx2 v[32:33], v[20:21], off offset:96
	v_pk_mul_f32 v[18:19], v[28:29], v[48:49] op_sel_hi:[1,0]
	v_pk_mul_f32 v[20:21], v[30:31], v[48:49] op_sel_hi:[1,0]
	s_waitcnt vmcnt(7)
	v_lshlrev_b32_e32 v22, 16, v162
	v_and_b32_e32 v23, 0xffff0000, v162
	v_lshlrev_b32_e32 v16, 16, v163
	v_and_b32_e32 v17, 0xffff0000, v163
	v_pk_mul_f32 v[18:19], v[18:19], v[22:23]
	v_pk_mul_f32 v[16:17], v[20:21], v[16:17]
	v_cvt_pk_bf16_f32 v18, v18, v19
	v_cvt_pk_bf16_f32 v19, v16, v17
	global_store_dwordx2 v[32:33], v[18:19], off offset:112
	s_cbranch_scc0 .LBB0_382
